# merged LDS waits, folded 0+x adds, hoisted next-phase first softmax group above the last tail MFMA in MLA/dense attention loops
# speedup vs baseline: 1.0122x; 1.0066x over previous
.LBB0_441:
	s_and_b32 s48, s33, 2
	s_add_i32 s4, s33, -1
	s_and_b32 s49, s4, 3
	s_mul_i32 s4, s48, 0x4800
	v_add_u32_e32 v168, s4, v184
	s_cmp_eq_u32 s33, 0
	ds_read_b128 v[164:167], v168 offset:96
	s_cselect_b64 s[6:7], -1, 0
	s_mulk_i32 s49, 0x4800
	s_and_b64 s[4:5], s[6:7], exec
	s_cselect_b32 s4, 0, s49
	v_add_u32_e32 v84, s4, v184
	v_exp_f32_e32 v64, v64
	v_exp_f32_e32 v65, v65
	s_nop 0
	v_add_f32_e32 v113, v65, v64
	v_cvt_pk_bf16_f32 v112, v64, v65
	ds_read_b128 v[186:189], v84 offset:9280
	ds_read_b128 v[190:193], v84 offset:9312
	ds_read_b128 v[194:197], v84 offset:13888
	ds_read_b128 v[198:201], v84 offset:13920
	s_waitcnt lgkmcnt(7)
	v_mfma_f32_32x32x16_bf16 v[80:95], v[80:83], v[148:151], 0
	v_exp_f32_e32 v64, v66
	v_exp_f32_e32 v65, v67
	v_add_f32_e32 v66, v64, v113
	v_add_f32_e32 v66, v65, v66
	v_cvt_pk_bf16_f32 v113, v64, v65
	s_waitcnt lgkmcnt(6)
	v_mfma_f32_32x32x16_bf16 v[80:95], v[108:111], v[152:155], v[80:95]
	v_exp_f32_e32 v64, v68
	v_exp_f32_e32 v65, v69
	v_add_f32_e32 v66, v64, v66
	v_cvt_pk_bf16_f32 v114, v64, v65
	v_add_f32_e32 v64, v65, v66
	s_waitcnt lgkmcnt(5)
	v_mfma_f32_32x32x16_bf16 v[80:95], v[104:107], v[156:159], v[80:95]
	v_exp_f32_e32 v65, v70
	v_exp_f32_e32 v66, v71
	v_add_f32_e32 v64, v65, v64
	v_cvt_pk_bf16_f32 v115, v65, v66
	v_add_f32_e32 v64, v66, v64
	s_waitcnt lgkmcnt(4)
	v_mfma_f32_32x32x16_bf16 v[80:95], v[164:167], v[160:163], v[80:95]
	v_exp_f32_e32 v65, v72
	v_exp_f32_e32 v66, v73
	v_add_f32_e32 v64, v65, v64
	v_cvt_pk_bf16_f32 v104, v65, v66
	v_add_f32_e32 v64, v66, v64
	s_waitcnt lgkmcnt(0)
	v_mfma_f32_32x32x16_bf16 v[16:31], v[186:189], v[96:99], v[16:31]
	v_exp_f32_e32 v65, v74
	v_exp_f32_e32 v66, v75
	v_add_f32_e32 v64, v65, v64
	v_cvt_pk_bf16_f32 v105, v65, v66
	v_add_f32_e32 v64, v66, v64
	v_mfma_f32_32x32x16_bf16 v[16:31], v[190:193], v[100:103], v[16:31]
	v_exp_f32_e32 v65, v76
	v_exp_f32_e32 v66, v77
	v_add_f32_e32 v64, v65, v64
	v_cvt_pk_bf16_f32 v106, v65, v66
	v_add_f32_e32 v64, v66, v64
	v_mfma_f32_32x32x16_bf16 v[0:15], v[194:197], v[96:99], v[0:15]
	v_exp_f32_e32 v65, v78
	v_exp_f32_e32 v66, v79
	v_add_f32_e32 v64, v65, v64
	v_cvt_pk_bf16_f32 v107, v65, v66
	v_add_f32_e32 v185, v66, v64
	v_exp_f32_e32 v68, v80
	v_exp_f32_e32 v69, v81
	s_nop 0
	v_add_f32_e32 v80, v69, v68
	v_cvt_pk_bf16_f32 v96, v68, v69
	v_mfma_f32_32x32x16_bf16 v[0:15], v[198:201], v[100:103], v[0:15]
	ds_read_b128 v[64:67], v168 offset:4608
	ds_read_b128 v[164:167], v168 offset:4640
	ds_read_b128 v[108:111], v168 offset:4672
	v_cmp_ge_f32_e32 vcc, s62, v185
	s_mov_b64 s[8:9], -1
	s_mov_b64 s[4:5], -1
	s_and_saveexec_b64 s[10:11], vcc
	v_cmp_gt_f32_e32 vcc, s75, v185
	s_and_b64 s[4:5], s[6:7], vcc
	s_orn2_b64 s[4:5], s[4:5], exec
	s_or_b64 exec, exec, s[10:11]
	ds_read_b128 v[186:189], v168 offset:4704
	s_waitcnt lgkmcnt(1)
	v_mfma_f32_32x32x16_bf16 v[64:79], v[64:67], v[116:119], 0
	ds_read_b128 v[190:193], v168 offset:9216
	ds_read_b128 v[194:197], v168 offset:9248
	ds_read_b128 v[198:201], v168 offset:13824
	ds_read_b128 v[230:233], v168 offset:13856
	v_exp_f32_e32 v81, v82
	v_exp_f32_e32 v82, v83
	v_add_f32_e32 v80, v81, v80
	v_add_f32_e32 v80, v82, v80
	v_cvt_pk_bf16_f32 v97, v81, v82
	v_mfma_f32_32x32x16_bf16 v[64:79], v[164:167], v[120:123], v[64:79]
	v_exp_f32_e32 v81, v84
	v_exp_f32_e32 v82, v85
	v_add_f32_e32 v80, v81, v80
	v_cvt_pk_bf16_f32 v98, v81, v82
	v_add_f32_e32 v80, v82, v80
	v_mfma_f32_32x32x16_bf16 v[64:79], v[108:111], v[124:127], v[64:79]
	v_exp_f32_e32 v81, v86
	v_exp_f32_e32 v82, v87
	v_add_f32_e32 v80, v81, v80
	v_cvt_pk_bf16_f32 v99, v81, v82
	v_add_f32_e32 v80, v82, v80
	s_waitcnt lgkmcnt(4)
	v_mfma_f32_32x32x16_bf16 v[64:79], v[186:189], v[128:131], v[64:79]
	v_exp_f32_e32 v81, v88
	v_exp_f32_e32 v82, v89
	v_add_f32_e32 v80, v81, v80
	v_cvt_pk_bf16_f32 v100, v81, v82
	v_add_f32_e32 v80, v82, v80
	s_waitcnt lgkmcnt(0)
	v_mfma_f32_32x32x16_bf16 v[48:63], v[190:193], v[112:115], v[48:63]
	v_exp_f32_e32 v81, v90
	v_exp_f32_e32 v82, v91
	v_add_f32_e32 v80, v81, v80
	v_cvt_pk_bf16_f32 v101, v81, v82
	v_add_f32_e32 v80, v82, v80
	v_mfma_f32_32x32x16_bf16 v[48:63], v[194:197], v[104:107], v[48:63]
	v_exp_f32_e32 v81, v92
	v_exp_f32_e32 v82, v93
	v_add_f32_e32 v80, v81, v80
	v_cvt_pk_bf16_f32 v102, v81, v82
	v_add_f32_e32 v80, v82, v80
	v_mfma_f32_32x32x16_bf16 v[32:47], v[198:201], v[112:115], v[32:47]
	v_exp_f32_e32 v81, v94
	v_exp_f32_e32 v82, v95
	v_add_f32_e32 v80, v81, v80
	v_cvt_pk_bf16_f32 v103, v81, v82
	v_add_f32_e32 v164, v82, v80
	v_exp_f32_e32 v64, v64
	v_exp_f32_e32 v65, v65
	s_nop 0
	v_add_f32_e32 v165, v65, v64
	v_cvt_pk_bf16_f32 v186, v64, v65
	v_mfma_f32_32x32x16_bf16 v[32:47], v[230:233], v[104:107], v[32:47]
	ds_read_b128 v[80:83], v168 offset:4608
	ds_read_b128 v[112:115], v168 offset:4640
	ds_read_b128 v[108:111], v168 offset:4672
	v_cndmask_b32_e64 v84, 0, 1, s[4:5]
	v_cmp_ne_u32_e64 s[4:5], 0, v84
	v_cmp_ge_f32_e32 vcc, s62, v164
	s_and_saveexec_b64 s[10:11], vcc
	v_cmp_gt_f32_e32 vcc, s75, v164
	s_and_b64 s[6:7], s[6:7], vcc
	s_orn2_b64 s[8:9], s[6:7], exec
	s_or_b64 exec, exec, s[10:11]
	v_cndmask_b32_e64 v84, 0, 1, s[8:9]
	v_cmp_ne_u32_e64 s[6:7], 0, v84
	ds_read_b128 v[104:107], v168 offset:4704
	s_waitcnt lgkmcnt(1)
	v_mfma_f32_32x32x16_bf16 v[80:95], v[80:83], v[148:151], 0
	ds_read_b128 v[190:193], v168 offset:9216
	ds_read_b128 v[194:197], v168 offset:9248
	ds_read_b128 v[198:201], v168 offset:13824
	ds_read_b128 v[230:233], v168 offset:13856
	v_exp_f32_e32 v64, v66
	v_exp_f32_e32 v65, v67
	v_add_f32_e32 v66, v64, v165
	v_add_f32_e32 v66, v65, v66
	v_cvt_pk_bf16_f32 v187, v64, v65
	v_mfma_f32_32x32x16_bf16 v[80:95], v[112:115], v[152:155], v[80:95]
	v_exp_f32_e32 v64, v68
	v_exp_f32_e32 v65, v69
	v_add_f32_e32 v66, v64, v66
	v_cvt_pk_bf16_f32 v188, v64, v65
	v_add_f32_e32 v64, v65, v66
	v_mfma_f32_32x32x16_bf16 v[80:95], v[108:111], v[156:159], v[80:95]
	v_exp_f32_e32 v65, v70
	v_exp_f32_e32 v66, v71
	v_add_f32_e32 v64, v65, v64
	v_cvt_pk_bf16_f32 v189, v65, v66
	v_add_f32_e32 v64, v66, v64
	s_waitcnt lgkmcnt(4)
	v_mfma_f32_32x32x16_bf16 v[80:95], v[104:107], v[160:163], v[80:95]
	v_exp_f32_e32 v65, v72
	v_exp_f32_e32 v66, v73
	v_add_f32_e32 v64, v65, v64
	v_cvt_pk_bf16_f32 v108, v65, v66
	v_add_f32_e32 v64, v66, v64
	s_waitcnt lgkmcnt(0)
	v_mfma_f32_32x32x16_bf16 v[16:31], v[190:193], v[96:99], v[16:31]
	v_exp_f32_e32 v65, v74
	v_exp_f32_e32 v66, v75
	v_add_f32_e32 v64, v65, v64
	v_cvt_pk_bf16_f32 v109, v65, v66
	v_add_f32_e32 v64, v66, v64
	v_mfma_f32_32x32x16_bf16 v[16:31], v[194:197], v[100:103], v[16:31]
	v_exp_f32_e32 v65, v76
	v_exp_f32_e32 v66, v77
	v_add_f32_e32 v64, v65, v64
	v_cvt_pk_bf16_f32 v110, v65, v66
	v_add_f32_e32 v64, v66, v64
	v_mfma_f32_32x32x16_bf16 v[0:15], v[198:201], v[96:99], v[0:15]
	v_exp_f32_e32 v65, v78
	v_exp_f32_e32 v66, v79
	v_add_f32_e32 v64, v65, v64
	v_cvt_pk_bf16_f32 v111, v65, v66
	v_add_f32_e32 v104, v66, v64
	v_exp_f32_e32 v68, v80
	v_exp_f32_e32 v69, v81
	s_nop 0
	v_add_f32_e32 v81, v69, v68
	v_cvt_pk_bf16_f32 v80, v68, v69
	v_mfma_f32_32x32x16_bf16 v[0:15], v[230:233], v[100:103], v[0:15]
	ds_read_b128 v[64:67], v168 offset:18432
	ds_read_b128 v[96:99], v168 offset:18464
	ds_read_b128 v[112:115], v168 offset:18496
	v_cmp_nge_f32_e64 s[8:9], s62, v104
	ds_read_b128 v[100:103], v168 offset:18528
	s_waitcnt lgkmcnt(1)
	v_mfma_f32_32x32x16_bf16 v[64:79], v[64:67], v[116:119], 0
	ds_read_b128 v[190:193], v168 offset:9280
	ds_read_b128 v[194:197], v168 offset:9312
	ds_read_b128 v[198:201], v168 offset:13888
	ds_read_b128 v[230:233], v168 offset:13920
	v_exp_f32_e32 v82, v82
	v_exp_f32_e32 v83, v83
	v_add_f32_e32 v81, v82, v81
	v_add_f32_e32 v105, v83, v81
	v_cvt_pk_bf16_f32 v81, v82, v83
	v_mfma_f32_32x32x16_bf16 v[64:79], v[96:99], v[120:123], v[64:79]
	v_exp_f32_e32 v82, v84
	v_exp_f32_e32 v83, v85
	v_add_f32_e32 v84, v82, v105
	v_cvt_pk_bf16_f32 v82, v82, v83
	v_add_f32_e32 v83, v83, v84
	v_mfma_f32_32x32x16_bf16 v[64:79], v[112:115], v[124:127], v[64:79]
	v_exp_f32_e32 v84, v86
	v_exp_f32_e32 v85, v87
	v_add_f32_e32 v86, v84, v83
	v_cvt_pk_bf16_f32 v83, v84, v85
	v_add_f32_e32 v84, v85, v86
	s_waitcnt lgkmcnt(4)
	v_mfma_f32_32x32x16_bf16 v[64:79], v[100:103], v[128:131], v[64:79]
	v_exp_f32_e32 v85, v88
	v_exp_f32_e32 v86, v89
	v_add_f32_e32 v87, v85, v84
	v_cvt_pk_bf16_f32 v84, v85, v86
	v_add_f32_e32 v85, v86, v87
	s_waitcnt lgkmcnt(0)
	v_mfma_f32_32x32x16_bf16 v[48:63], v[190:193], v[186:189], v[48:63]
	v_exp_f32_e32 v86, v90
	v_exp_f32_e32 v87, v91
	v_add_f32_e32 v88, v86, v85
	v_cvt_pk_bf16_f32 v85, v86, v87
	v_add_f32_e32 v86, v87, v88
	v_mfma_f32_32x32x16_bf16 v[48:63], v[194:197], v[108:111], v[48:63]
	v_exp_f32_e32 v87, v92
	v_exp_f32_e32 v88, v93
	v_add_f32_e32 v89, v87, v86
	v_cvt_pk_bf16_f32 v86, v87, v88
	v_add_f32_e32 v87, v88, v89
	v_mfma_f32_32x32x16_bf16 v[32:47], v[198:201], v[186:189], v[32:47]
	v_exp_f32_e32 v88, v94
	v_exp_f32_e32 v89, v95
	v_add_f32_e32 v90, v88, v87
	v_cvt_pk_bf16_f32 v87, v88, v89
	v_add_f32_e32 v105, v89, v90
	v_mfma_f32_32x32x16_bf16 v[32:47], v[230:233], v[108:111], v[32:47]
	ds_read_b128 v[96:99], v168 offset:18432
	ds_read_b128 v[92:95], v168 offset:18464
	ds_read_b128 v[88:91], v168 offset:18496
	v_cmp_nge_f32_e64 s[10:11], s62, v105
	s_waitcnt lgkmcnt(0)
	s_barrier
	s_cmpk_gt_u32 s33, 0xfc
	s_cbranch_scc1 .LBB0_447
	v_add_u32_e32 v100, s49, v173
	s_waitcnt vmcnt(1)
	ds_write_b128 v100, v[140:143]
	s_waitcnt vmcnt(0)
	ds_write_b128 v100, v[144:147] offset:9216

.LBB0_449:
	v_add_f32_e32 v101, v179, v164
	ds_read_b128 v[164:167], v168 offset:18528
	s_or_b64 s[4:5], s[6:7], s[4:5]
	v_add_f32_e32 v100, v178, v185
	s_or_b64 s[4:5], s[4:5], s[8:9]
	s_or_b64 s[4:5], s[4:5], s[10:11]
	v_pk_add_f32 v[182:183], v[100:101], v[104:105]
	s_xor_b32 s8, s48, 2
	v_exp_f32_e32 v64, v64
	v_exp_f32_e32 v65, v65
	s_nop 0
	v_add_f32_e32 v185, v65, v64
	v_cvt_pk_bf16_f32 v64, v64, v65
	s_waitcnt lgkmcnt(3)
	v_mfma_f32_32x32x16_bf16 v[100:115], v[96:99], v[148:151], 0
	ds_read_b128 v[178:181], v168 offset:9280
	ds_read_b128 v[186:189], v168 offset:9312
	ds_read_b128 v[190:193], v168 offset:13888
	ds_read_b128 v[194:197], v168 offset:13920
	v_exp_f32_e32 v65, v66
	v_exp_f32_e32 v66, v67
	v_add_f32_e32 v67, v65, v185
	v_add_f32_e32 v67, v66, v67
	v_cvt_pk_bf16_f32 v65, v65, v66
	s_waitcnt lgkmcnt(6)
	v_mfma_f32_32x32x16_bf16 v[100:115], v[92:95], v[152:155], v[100:115]
	v_exp_f32_e32 v66, v68
	v_exp_f32_e32 v68, v69
	v_add_f32_e32 v67, v66, v67
	v_cvt_pk_bf16_f32 v66, v66, v68
	v_add_f32_e32 v67, v68, v67
	s_waitcnt lgkmcnt(5)
	v_mfma_f32_32x32x16_bf16 v[100:115], v[88:91], v[156:159], v[100:115]
	v_exp_f32_e32 v68, v70
	v_exp_f32_e32 v69, v71
	v_add_f32_e32 v70, v68, v67
	v_cvt_pk_bf16_f32 v67, v68, v69
	v_add_f32_e32 v68, v69, v70
	s_waitcnt lgkmcnt(4)
	v_mfma_f32_32x32x16_bf16 v[100:115], v[164:167], v[160:163], v[100:115]
	v_exp_f32_e32 v69, v72
	v_exp_f32_e32 v70, v73
	v_add_f32_e32 v71, v69, v68
	v_cvt_pk_bf16_f32 v68, v69, v70
	v_add_f32_e32 v69, v70, v71
	s_waitcnt lgkmcnt(0)
	v_mfma_f32_32x32x16_bf16 v[16:31], v[178:181], v[80:83], v[16:31]
	v_exp_f32_e32 v70, v74
	v_exp_f32_e32 v71, v75
	v_add_f32_e32 v72, v70, v69
	v_cvt_pk_bf16_f32 v69, v70, v71
	v_add_f32_e32 v70, v71, v72
	v_mfma_f32_32x32x16_bf16 v[16:31], v[186:189], v[84:87], v[16:31]
	v_exp_f32_e32 v71, v76
	v_exp_f32_e32 v72, v77
	v_add_f32_e32 v73, v71, v70
	v_cvt_pk_bf16_f32 v70, v71, v72
	v_add_f32_e32 v71, v72, v73
	v_mfma_f32_32x32x16_bf16 v[0:15], v[190:193], v[80:83], v[0:15]
	v_exp_f32_e32 v72, v78
	v_exp_f32_e32 v73, v79
	v_add_f32_e32 v74, v72, v71
	v_cvt_pk_bf16_f32 v71, v72, v73
	v_add_f32_e32 v198, v73, v74
	v_exp_f32_e32 v88, v100
	v_exp_f32_e32 v89, v101
	s_nop 0
	v_add_f32_e32 v165, v89, v88
	v_cvt_pk_bf16_f32 v164, v88, v89
	v_mfma_f32_32x32x16_bf16 v[0:15], v[194:197], v[84:87], v[0:15]
	ds_read_b128 v[72:75], v168 offset:23040
	ds_read_b128 v[76:79], v168 offset:23072
	ds_read_b128 v[80:83], v168 offset:23104
	v_cmp_nge_f32_e32 vcc, s62, v198
	ds_read_b128 v[84:87], v168 offset:23136
	v_exp_f32_e32 v166, v102
	v_exp_f32_e32 v167, v103
	s_waitcnt lgkmcnt(1)
	v_mfma_f32_32x32x16_bf16 v[88:103], v[72:75], v[116:119], 0
	ds_read_b128 v[178:181], v168 offset:27648
	ds_read_b128 v[186:189], v168 offset:27680
	ds_read_b128 v[190:193], v168 offset:32256
	ds_read_b128 v[194:197], v168 offset:32288
	v_add_f32_e32 v72, v166, v165
	v_add_f32_e32 v72, v167, v72
	v_cvt_pk_bf16_f32 v165, v166, v167
	v_mfma_f32_32x32x16_bf16 v[88:103], v[76:79], v[120:123], v[88:103]
	v_exp_f32_e32 v73, v104
	v_exp_f32_e32 v74, v105
	v_add_f32_e32 v72, v73, v72
	v_cvt_pk_bf16_f32 v166, v73, v74
	v_add_f32_e32 v72, v74, v72
	v_mfma_f32_32x32x16_bf16 v[88:103], v[80:83], v[124:127], v[88:103]
	v_exp_f32_e32 v73, v106
	v_exp_f32_e32 v74, v107
	v_add_f32_e32 v72, v73, v72
	v_cvt_pk_bf16_f32 v167, v73, v74
	v_add_f32_e32 v72, v74, v72
	s_waitcnt lgkmcnt(4)
	v_mfma_f32_32x32x16_bf16 v[88:103], v[84:87], v[128:131], v[88:103]
	v_exp_f32_e32 v73, v108
	v_exp_f32_e32 v74, v109
	v_add_f32_e32 v75, v73, v72
	v_cvt_pk_bf16_f32 v72, v73, v74
	v_add_f32_e32 v73, v74, v75
	s_waitcnt lgkmcnt(0)
	v_mfma_f32_32x32x16_bf16 v[48:63], v[178:181], v[64:67], v[48:63]
	v_exp_f32_e32 v74, v110
	v_exp_f32_e32 v75, v111
	v_add_f32_e32 v76, v74, v73
	v_cvt_pk_bf16_f32 v73, v74, v75
	v_add_f32_e32 v74, v75, v76
	v_mfma_f32_32x32x16_bf16 v[48:63], v[186:189], v[68:71], v[48:63]
	v_exp_f32_e32 v75, v112
	v_exp_f32_e32 v76, v113
	v_add_f32_e32 v77, v75, v74
	v_cvt_pk_bf16_f32 v74, v75, v76
	v_add_f32_e32 v75, v76, v77
	v_mfma_f32_32x32x16_bf16 v[32:47], v[190:193], v[64:67], v[32:47]
	v_exp_f32_e32 v76, v114
	v_exp_f32_e32 v77, v115
	v_add_f32_e32 v78, v76, v75
	v_cvt_pk_bf16_f32 v75, v76, v77
	v_add_f32_e32 v199, v77, v78
	v_exp_f32_e32 v76, v88
	v_exp_f32_e32 v77, v89
	s_nop 0
	v_add_f32_e32 v113, v77, v76
	v_cvt_pk_bf16_f32 v112, v76, v77
	v_mfma_f32_32x32x16_bf16 v[32:47], v[194:197], v[68:71], v[32:47]
	ds_read_b128 v[64:67], v168 offset:23040
	ds_read_b128 v[104:107], v168 offset:23072
	ds_read_b128 v[108:111], v168 offset:23104
	s_or_b64 s[6:7], s[4:5], vcc
	v_cmp_nge_f32_e32 vcc, s62, v199
	v_pk_add_f32 v[182:183], v[182:183], v[198:199]
	ds_read_b128 v[68:71], v168 offset:23136
	v_exp_f32_e32 v114, v90
	v_exp_f32_e32 v115, v91
	s_waitcnt lgkmcnt(1)
	v_mfma_f32_32x32x16_bf16 v[76:91], v[64:67], v[148:151], 0
	ds_read_b128 v[178:181], v168 offset:27648
	ds_read_b128 v[186:189], v168 offset:27680
	ds_read_b128 v[190:193], v168 offset:32256
	ds_read_b128 v[194:197], v168 offset:32288
	v_add_f32_e32 v64, v114, v113
	v_add_f32_e32 v64, v115, v64
	v_cvt_pk_bf16_f32 v113, v114, v115
	v_mfma_f32_32x32x16_bf16 v[76:91], v[104:107], v[152:155], v[76:91]
	v_exp_f32_e32 v65, v92
	v_exp_f32_e32 v66, v93
	v_add_f32_e32 v64, v65, v64
	v_cvt_pk_bf16_f32 v114, v65, v66
	v_add_f32_e32 v64, v66, v64
	v_mfma_f32_32x32x16_bf16 v[76:91], v[108:111], v[156:159], v[76:91]
	v_exp_f32_e32 v65, v94
	v_exp_f32_e32 v66, v95
	v_add_f32_e32 v64, v65, v64
	v_cvt_pk_bf16_f32 v115, v65, v66
	v_add_f32_e32 v64, v66, v64
	s_waitcnt lgkmcnt(4)
	v_mfma_f32_32x32x16_bf16 v[76:91], v[68:71], v[160:163], v[76:91]
	v_exp_f32_e32 v65, v96
	v_exp_f32_e32 v66, v97
	v_add_f32_e32 v64, v65, v64
	v_cvt_pk_bf16_f32 v92, v65, v66
	v_add_f32_e32 v64, v66, v64
	s_waitcnt lgkmcnt(0)
	v_mfma_f32_32x32x16_bf16 v[16:31], v[178:181], v[164:167], v[16:31]
	v_exp_f32_e32 v65, v98
	v_exp_f32_e32 v66, v99
	v_add_f32_e32 v64, v65, v64
	v_cvt_pk_bf16_f32 v93, v65, v66
	v_add_f32_e32 v64, v66, v64
	v_mfma_f32_32x32x16_bf16 v[16:31], v[186:189], v[72:75], v[16:31]
	v_exp_f32_e32 v65, v100
	v_exp_f32_e32 v66, v101
	v_add_f32_e32 v64, v65, v64
	v_cvt_pk_bf16_f32 v94, v65, v66
	v_add_f32_e32 v64, v66, v64
	v_mfma_f32_32x32x16_bf16 v[0:15], v[190:193], v[164:167], v[0:15]
	v_exp_f32_e32 v65, v102
	v_exp_f32_e32 v66, v103
	v_add_f32_e32 v64, v65, v64
	v_cvt_pk_bf16_f32 v95, v65, v66
	v_add_f32_e32 v198, v66, v64
	s_mulk_i32 s8, 0x4800
	v_exp_f32_e32 v68, v76
	v_exp_f32_e32 v69, v77
	s_nop 0
	v_add_f32_e32 v97, v69, v68
	v_cvt_pk_bf16_f32 v96, v68, v69
	v_mfma_f32_32x32x16_bf16 v[0:15], v[194:197], v[72:75], v[0:15]
	v_add_u32_e32 v185, s8, v184
	ds_read_b128 v[64:67], v185
	ds_read_b128 v[100:103], v185 offset:32
	ds_read_b128 v[104:107], v185 offset:64
	v_cmp_nge_f32_e64 s[4:5], s62, v198
	ds_read_b128 v[108:111], v185 offset:96
	s_or_b64 s[6:7], s[6:7], vcc
	v_exp_f32_e32 v98, v78
	v_exp_f32_e32 v99, v79
	s_waitcnt lgkmcnt(1)
	v_mfma_f32_32x32x16_bf16 v[64:79], v[64:67], v[116:119], 0
	ds_read_b128 v[164:167], v168 offset:27712
	ds_read_b128 v[178:181], v168 offset:27744
	ds_read_b128 v[186:189], v168 offset:32320
	ds_read_b128 v[190:193], v168 offset:32352
	v_add_f32_e32 v97, v98, v97
	v_add_f32_e32 v168, v99, v97
	v_cvt_pk_bf16_f32 v97, v98, v99
	v_mfma_f32_32x32x16_bf16 v[64:79], v[100:103], v[120:123], v[64:79]
	v_exp_f32_e32 v80, v80
	v_exp_f32_e32 v81, v81
	v_add_f32_e32 v99, v80, v168
	v_cvt_pk_bf16_f32 v98, v80, v81
	v_add_f32_e32 v80, v81, v99
	v_mfma_f32_32x32x16_bf16 v[64:79], v[104:107], v[124:127], v[64:79]
	v_exp_f32_e32 v81, v82
	v_exp_f32_e32 v82, v83
	v_add_f32_e32 v80, v81, v80
	v_cvt_pk_bf16_f32 v99, v81, v82
	v_add_f32_e32 v80, v82, v80
	s_waitcnt lgkmcnt(4)
	v_mfma_f32_32x32x16_bf16 v[64:79], v[108:111], v[128:131], v[64:79]
	v_exp_f32_e32 v81, v84
	v_exp_f32_e32 v82, v85
	v_add_f32_e32 v80, v81, v80
	v_cvt_pk_bf16_f32 v100, v81, v82
	v_add_f32_e32 v80, v82, v80
	s_waitcnt lgkmcnt(0)
	v_mfma_f32_32x32x16_bf16 v[48:63], v[164:167], v[112:115], v[48:63]
	v_exp_f32_e32 v81, v86
	v_exp_f32_e32 v82, v87
	v_add_f32_e32 v80, v81, v80
	v_cvt_pk_bf16_f32 v101, v81, v82
	v_add_f32_e32 v80, v82, v80
	v_mfma_f32_32x32x16_bf16 v[48:63], v[178:181], v[92:95], v[48:63]
	v_exp_f32_e32 v81, v88
	v_exp_f32_e32 v82, v89
	v_add_f32_e32 v80, v81, v80
	v_cvt_pk_bf16_f32 v102, v81, v82
	v_add_f32_e32 v80, v82, v80
	v_mfma_f32_32x32x16_bf16 v[32:47], v[186:189], v[112:115], v[32:47]
	v_exp_f32_e32 v81, v90
	v_exp_f32_e32 v82, v91
	v_add_f32_e32 v80, v81, v80
	v_cvt_pk_bf16_f32 v103, v81, v82
	v_add_f32_e32 v199, v82, v80
	v_mfma_f32_32x32x16_bf16 v[32:47], v[190:193], v[92:95], v[32:47]
	ds_read_b128 v[80:83], v185
	ds_read_b128 v[108:111], v185 offset:32
	ds_read_b128 v[104:107], v185 offset:64
	s_or_b64 s[4:5], s[6:7], s[4:5]
	v_cmp_nge_f32_e32 vcc, s62, v199
	s_or_b64 s[4:5], s[4:5], vcc
	s_cmp_lg_u64 s[4:5], 0
	s_cselect_b64 s[4:5], -1, 0
	s_or_b64 s[42:43], s[42:43], s[4:5]
	v_pk_add_f32 v[178:179], v[182:183], v[198:199]
	s_waitcnt lgkmcnt(0)
	s_barrier
	s_add_u32 s46, s46, 0x8000
	s_addc_u32 s47, s47, 0
	s_and_b64 vcc, exec, s[44:45]
	s_cbranch_vccnz .LBB0_451
	s_mov_b32 s33, s14
	s_branch .LBB0_437

.LBB0_927:
	s_add_i32 s6, s61, -1
	s_and_b32 s77, s61, 2
	s_and_b32 s79, s6, 3
	s_cmp_eq_u32 s61, 0
	s_cselect_b64 s[8:9], -1, 0
	s_mulk_i32 s79, 0x5800
	s_and_b64 s[6:7], s[8:9], exec
	s_mul_i32 s78, s77, 0x5800
	s_cselect_b32 s6, 0, s79
	s_add_i32 s76, s78, 0
	v_add_u32_e32 v199, s76, v241
	v_add_u32_e32 v210, s6, v244
	v_exp_f32_e32 v64, v64
	v_exp_f32_e32 v65, v65
	s_nop 0
	v_add_f32_e32 v84, v65, v64
	v_cvt_pk_bf16_f32 v178, v64, v65
	v_exp_f32_e32 v64, v66
	ds_read_b128 v[182:185], v199 offset:96
	ds_read_b128 v[246:249], v199 offset:128
	ds_read_b128 v[250:253], v199 offset:160
	v_exp_f32_e32 v65, v67
	v_add_f32_e32 v66, v64, v84
	s_waitcnt lgkmcnt(4)
	v_mfma_f32_32x32x16_bf16 v[80:95], v[80:83], v[122:125], 0
	v_add_f32_e32 v66, v65, v66
	v_cvt_pk_bf16_f32 v179, v64, v65
	v_mfma_f32_32x32x16_bf16 v[80:95], v[174:177], v[126:129], v[80:95]
	v_exp_f32_e32 v64, v68
	v_exp_f32_e32 v65, v69
	v_add_f32_e32 v66, v64, v66
	v_add_f32_e32 v66, v65, v66
	v_cvt_pk_bf16_f32 v180, v64, v65
	s_waitcnt lgkmcnt(3)
	v_mfma_f32_32x32x16_bf16 v[80:95], v[170:173], v[130:133], v[80:95]
	v_exp_f32_e32 v64, v70
	v_exp_f32_e32 v65, v71
	v_add_f32_e32 v66, v64, v66
	v_add_f32_e32 v170, v65, v66
	v_cvt_pk_bf16_f32 v181, v64, v65
	s_waitcnt lgkmcnt(0)
	v_mfma_f32_32x32x16_bf16 v[80:95], v[182:185], v[134:137], v[80:95]
	ds_read_b128 v[64:67], v210 offset:13376
	ds_read_b128 v[68:71], v210 offset:13408
	ds_read_b128 v[174:177], v210 offset:17984
	ds_read_b128 v[218:221], v210 offset:18016
	v_exp_f32_e32 v72, v72
	v_exp_f32_e32 v73, v73
	v_add_f32_e32 v170, v72, v170
	v_add_f32_e32 v171, v73, v170
	v_cvt_pk_bf16_f32 v170, v72, v73
	v_mfma_f32_32x32x16_bf16 v[80:95], v[246:249], v[154:157], v[80:95]
	v_exp_f32_e32 v72, v74
	v_exp_f32_e32 v73, v75
	v_add_f32_e32 v74, v72, v171
	v_add_f32_e32 v74, v73, v74
	v_cvt_pk_bf16_f32 v171, v72, v73
	v_mfma_f32_32x32x16_bf16 v[80:95], v[250:253], v[158:161], v[80:95]
	v_exp_f32_e32 v72, v76
	v_exp_f32_e32 v73, v77
	v_add_f32_e32 v74, v72, v74
	v_add_f32_e32 v74, v73, v74
	v_cvt_pk_bf16_f32 v172, v72, v73
	s_waitcnt lgkmcnt(0)
	v_mfma_f32_32x32x16_bf16 v[16:31], v[64:67], v[162:165], v[16:31]
	v_exp_f32_e32 v64, v78
	v_exp_f32_e32 v65, v79
	v_add_f32_e32 v66, v64, v74
	v_add_f32_e32 v246, v65, v66
	v_cvt_pk_bf16_f32 v173, v64, v65
	v_mfma_f32_32x32x16_bf16 v[0:15], v[174:177], v[162:165], v[0:15]
	ds_read_b128 v[64:67], v199 offset:6656
	ds_read_b128 v[182:185], v199 offset:6688
	ds_read_b128 v[174:177], v199 offset:6720
	v_cmp_ge_f32_e32 vcc, s48, v246
	s_mov_b64 s[10:11], -1
	s_mov_b64 s[6:7], -1
	v_mfma_f32_32x32x16_bf16 v[16:31], v[68:71], v[166:169], v[16:31]
	v_exp_f32_e32 v68, v80
	v_exp_f32_e32 v69, v81
	s_nop 0
	v_add_f32_e32 v70, v69, v68
	v_cvt_pk_bf16_f32 v162, v68, v69
	v_exp_f32_e32 v80, v82
	v_exp_f32_e32 v81, v83
	v_add_f32_e32 v82, v80, v70
	v_mfma_f32_32x32x16_bf16 v[0:15], v[218:221], v[166:169], v[0:15]
	s_and_saveexec_b64 s[12:13], vcc
	v_cmp_gt_f32_e32 vcc, s49, v246
	s_and_b64 s[6:7], s[8:9], vcc
	s_orn2_b64 s[6:7], s[6:7], exec
	s_or_b64 exec, exec, s[12:13]
	v_add_u32_e32 v211, s76, v243
	ds_read_b128 v[166:169], v199 offset:6752
	ds_read_b128 v[218:221], v199 offset:6784
	ds_read_b128 v[248:251], v199 offset:6816
	s_waitcnt lgkmcnt(3)
	v_mfma_f32_32x32x16_bf16 v[64:79], v[64:67], v[98:101], 0
	v_add_f32_e32 v82, v81, v82
	v_cvt_pk_bf16_f32 v163, v80, v81
	v_mfma_f32_32x32x16_bf16 v[64:79], v[182:185], v[102:105], v[64:79]
	v_exp_f32_e32 v80, v84
	v_exp_f32_e32 v81, v85
	v_add_f32_e32 v82, v80, v82
	v_add_f32_e32 v82, v81, v82
	v_cvt_pk_bf16_f32 v164, v80, v81
	v_mfma_f32_32x32x16_bf16 v[64:79], v[174:177], v[106:109], v[64:79]
	v_exp_f32_e32 v80, v86
	v_exp_f32_e32 v81, v87
	v_add_f32_e32 v82, v80, v82
	v_add_f32_e32 v174, v81, v82
	v_cvt_pk_bf16_f32 v165, v80, v81
	s_waitcnt lgkmcnt(0)
	v_mfma_f32_32x32x16_bf16 v[64:79], v[166:169], v[110:113], v[64:79]
	ds_read_b128 v[80:83], v211 offset:13312
	ds_read_b128 v[84:87], v211 offset:13344
	ds_read_b128 v[182:185], v211 offset:17920
	ds_read_b128 v[222:225], v211 offset:17952
	v_exp_f32_e32 v88, v88
	v_exp_f32_e32 v89, v89
	v_add_f32_e32 v166, v88, v174
	v_add_f32_e32 v166, v89, v166
	v_cvt_pk_bf16_f32 v174, v88, v89
	v_mfma_f32_32x32x16_bf16 v[64:79], v[218:221], v[114:117], v[64:79]
	v_exp_f32_e32 v88, v90
	v_exp_f32_e32 v89, v91
	v_add_f32_e32 v90, v88, v166
	v_add_f32_e32 v90, v89, v90
	v_cvt_pk_bf16_f32 v175, v88, v89
	v_mfma_f32_32x32x16_bf16 v[64:79], v[248:251], v[118:121], v[64:79]
	v_exp_f32_e32 v88, v92
	v_exp_f32_e32 v89, v93
	v_add_f32_e32 v90, v88, v90
	v_add_f32_e32 v90, v89, v90
	v_cvt_pk_bf16_f32 v176, v88, v89
	s_waitcnt lgkmcnt(0)
	v_mfma_f32_32x32x16_bf16 v[48:63], v[80:83], v[178:181], v[48:63]
	v_exp_f32_e32 v80, v94
	v_exp_f32_e32 v81, v95
	v_add_f32_e32 v82, v80, v90
	v_add_f32_e32 v247, v81, v82
	v_cvt_pk_bf16_f32 v177, v80, v81
	v_mfma_f32_32x32x16_bf16 v[32:47], v[182:185], v[178:181], v[32:47]
	ds_read_b128 v[80:83], v199 offset:6656
	ds_read_b128 v[182:185], v199 offset:6688
	ds_read_b128 v[178:181], v199 offset:6720
	v_cmp_ge_f32_e32 vcc, s48, v247
	v_mfma_f32_32x32x16_bf16 v[48:63], v[84:87], v[170:173], v[48:63]
	v_cndmask_b32_e64 v84, 0, 1, s[6:7]
	v_cmp_ne_u32_e64 s[6:7], 0, v84
	v_mfma_f32_32x32x16_bf16 v[32:47], v[222:225], v[170:173], v[32:47]
	s_and_saveexec_b64 s[12:13], vcc
	v_cmp_gt_f32_e32 vcc, s49, v247
	s_and_b64 s[8:9], s[8:9], vcc
	s_orn2_b64 s[10:11], s[8:9], exec
	s_or_b64 exec, exec, s[12:13]
	v_cndmask_b32_e64 v84, 0, 1, s[10:11]
	v_cmp_ne_u32_e64 s[8:9], 0, v84
	v_exp_f32_e32 v64, v64
	v_exp_f32_e32 v65, v65
	s_nop 0
	v_add_f32_e32 v84, v65, v64
	v_cvt_pk_bf16_f32 v166, v64, v65
	v_exp_f32_e32 v64, v66
	ds_read_b128 v[170:173], v199 offset:6752
	ds_read_b128 v[218:221], v199 offset:6784
	ds_read_b128 v[222:225], v199 offset:6816
	v_exp_f32_e32 v65, v67
	v_add_f32_e32 v66, v64, v84
	s_waitcnt lgkmcnt(3)
	v_mfma_f32_32x32x16_bf16 v[80:95], v[80:83], v[122:125], 0
	v_add_f32_e32 v66, v65, v66
	v_cvt_pk_bf16_f32 v167, v64, v65
	v_mfma_f32_32x32x16_bf16 v[80:95], v[182:185], v[126:129], v[80:95]
	v_exp_f32_e32 v64, v68
	v_exp_f32_e32 v65, v69
	v_add_f32_e32 v66, v64, v66
	v_add_f32_e32 v66, v65, v66
	v_cvt_pk_bf16_f32 v168, v64, v65
	v_mfma_f32_32x32x16_bf16 v[80:95], v[178:181], v[130:133], v[80:95]
	v_exp_f32_e32 v64, v70
	v_exp_f32_e32 v65, v71
	v_add_f32_e32 v66, v64, v66
	v_add_f32_e32 v178, v65, v66
	v_cvt_pk_bf16_f32 v169, v64, v65
	s_waitcnt lgkmcnt(0)
	v_mfma_f32_32x32x16_bf16 v[80:95], v[170:173], v[134:137], v[80:95]
	ds_read_b128 v[64:67], v211 offset:13312
	ds_read_b128 v[68:71], v211 offset:13344
	ds_read_b128 v[182:185], v211 offset:17920
	ds_read_b128 v[248:251], v211 offset:17952
	v_exp_f32_e32 v72, v72
	v_exp_f32_e32 v73, v73
	v_add_f32_e32 v170, v72, v178
	v_add_f32_e32 v170, v73, v170
	v_cvt_pk_bf16_f32 v178, v72, v73
	v_mfma_f32_32x32x16_bf16 v[80:95], v[218:221], v[154:157], v[80:95]
	v_exp_f32_e32 v72, v74
	v_exp_f32_e32 v73, v75
	v_add_f32_e32 v74, v72, v170
	v_add_f32_e32 v74, v73, v74
	v_cvt_pk_bf16_f32 v179, v72, v73
	v_mfma_f32_32x32x16_bf16 v[80:95], v[222:225], v[158:161], v[80:95]
	v_exp_f32_e32 v72, v76
	v_exp_f32_e32 v73, v77
	v_add_f32_e32 v74, v72, v74
	v_add_f32_e32 v74, v73, v74
	v_cvt_pk_bf16_f32 v180, v72, v73
	s_waitcnt lgkmcnt(0)
	v_mfma_f32_32x32x16_bf16 v[16:31], v[64:67], v[162:165], v[16:31]
	v_exp_f32_e32 v64, v78
	v_exp_f32_e32 v65, v79
	v_add_f32_e32 v66, v64, v74
	v_add_f32_e32 v210, v65, v66
	v_cvt_pk_bf16_f32 v181, v64, v65
	v_mfma_f32_32x32x16_bf16 v[0:15], v[182:185], v[162:165], v[0:15]
	v_add_u32_e32 v226, s78, v242
	ds_read_b128 v[64:67], v226 offset:22528
	ds_read_b128 v[170:173], v226 offset:22560
	ds_read_b128 v[182:185], v226 offset:22592
	v_cmp_nge_f32_e64 s[10:11], s48, v210
	v_mfma_f32_32x32x16_bf16 v[16:31], v[68:71], v[174:177], v[16:31]
	v_exp_f32_e32 v68, v80
	v_exp_f32_e32 v69, v81
	s_nop 0
	v_add_f32_e32 v70, v69, v68
	v_cvt_pk_bf16_f32 v162, v68, v69
	v_exp_f32_e32 v80, v82
	v_exp_f32_e32 v81, v83
	v_add_f32_e32 v82, v80, v70
	v_mfma_f32_32x32x16_bf16 v[0:15], v[248:251], v[174:177], v[0:15]
	ds_read_b128 v[174:177], v226 offset:22624
	ds_read_b128 v[218:221], v226 offset:22656
	ds_read_b128 v[222:225], v226 offset:22688
	s_waitcnt lgkmcnt(3)
	v_mfma_f32_32x32x16_bf16 v[64:79], v[64:67], v[98:101], 0
	v_add_f32_e32 v82, v81, v82
	v_cvt_pk_bf16_f32 v163, v80, v81
	v_mfma_f32_32x32x16_bf16 v[64:79], v[170:173], v[102:105], v[64:79]
	v_exp_f32_e32 v80, v84
	v_exp_f32_e32 v81, v85
	v_add_f32_e32 v82, v80, v82
	v_add_f32_e32 v82, v81, v82
	v_cvt_pk_bf16_f32 v164, v80, v81
	v_mfma_f32_32x32x16_bf16 v[64:79], v[182:185], v[106:109], v[64:79]
	v_exp_f32_e32 v80, v86
	v_exp_f32_e32 v81, v87
	v_add_f32_e32 v82, v80, v82
	v_add_f32_e32 v170, v81, v82
	v_cvt_pk_bf16_f32 v165, v80, v81
	s_waitcnt lgkmcnt(0)
	v_mfma_f32_32x32x16_bf16 v[64:79], v[174:177], v[110:113], v[64:79]
	ds_read_b128 v[80:83], v211 offset:13376
	ds_read_b128 v[84:87], v211 offset:13408
	ds_read_b128 v[182:185], v211 offset:17984
	ds_read_b128 v[248:251], v211 offset:18016
	v_exp_f32_e32 v88, v88
	v_exp_f32_e32 v89, v89
	v_add_f32_e32 v170, v88, v170
	v_add_f32_e32 v171, v89, v170
	v_cvt_pk_bf16_f32 v170, v88, v89
	v_mfma_f32_32x32x16_bf16 v[64:79], v[218:221], v[114:117], v[64:79]
	v_exp_f32_e32 v88, v90
	v_exp_f32_e32 v89, v91
	v_add_f32_e32 v90, v88, v171
	v_add_f32_e32 v90, v89, v90
	v_cvt_pk_bf16_f32 v171, v88, v89
	v_mfma_f32_32x32x16_bf16 v[64:79], v[222:225], v[118:121], v[64:79]
	v_exp_f32_e32 v88, v92
	v_exp_f32_e32 v89, v93
	v_add_f32_e32 v90, v88, v90
	v_add_f32_e32 v90, v89, v90
	v_cvt_pk_bf16_f32 v172, v88, v89
	s_waitcnt lgkmcnt(0)
	v_mfma_f32_32x32x16_bf16 v[48:63], v[80:83], v[166:169], v[48:63]
	v_exp_f32_e32 v80, v94
	v_exp_f32_e32 v81, v95
	v_add_f32_e32 v82, v80, v90
	v_add_f32_e32 v211, v81, v82
	v_cvt_pk_bf16_f32 v173, v80, v81
	v_mfma_f32_32x32x16_bf16 v[32:47], v[182:185], v[166:169], v[32:47]
	ds_read_b128 v[80:83], v226 offset:22528
	ds_read_b128 v[182:185], v226 offset:22560
	ds_read_b128 v[174:177], v226 offset:22592
	v_cmp_nge_f32_e64 s[12:13], s48, v211
	v_mfma_f32_32x32x16_bf16 v[48:63], v[84:87], v[178:181], v[48:63]
	v_mfma_f32_32x32x16_bf16 v[32:47], v[248:251], v[178:181], v[32:47]
	s_waitcnt lgkmcnt(0)
	s_barrier
	s_cmpk_gt_u32 s61, 0xfc
	s_cbranch_scc1 .LBB0_933
	s_add_i32 s24, s79, 0
	v_add_u32_e32 v84, s24, v238
	v_add_u32_e32 v85, s24, v245
	v_add_u32_e32 v86, s24, v198
	s_waitcnt vmcnt(1)
	ds_write_b128 v84, v[150:153]
	s_waitcnt vmcnt(0)
	ds_write_b64 v85, v[190:191] offset:128
	ds_write_b128 v86, v[138:141] offset:13312

.LBB0_935:
	s_or_b64 s[6:7], s[8:9], s[6:7]
	v_add_f32_e32 v84, v204, v246
	v_add_f32_e32 v85, v205, v247
	s_or_b64 s[6:7], s[6:7], s[10:11]
	s_or_b64 s[6:7], s[6:7], s[12:13]
	v_pk_add_f32 v[178:179], v[84:85], v[210:211]
	s_xor_b32 s10, s77, 2
	v_add_u32_e32 v222, s78, v244
	v_exp_f32_e32 v64, v64
	v_exp_f32_e32 v65, v65
	s_nop 0
	v_add_f32_e32 v84, v65, v64
	v_cvt_pk_bf16_f32 v166, v64, v65
	v_exp_f32_e32 v64, v66
	ds_read_b128 v[204:207], v199 offset:22624
	ds_read_b128 v[208:211], v199 offset:22656
	ds_read_b128 v[218:221], v199 offset:22688
	v_exp_f32_e32 v65, v67
	v_add_f32_e32 v66, v64, v84
	s_waitcnt lgkmcnt(5)
	v_mfma_f32_32x32x16_bf16 v[80:95], v[80:83], v[122:125], 0
	v_add_f32_e32 v66, v65, v66
	v_cvt_pk_bf16_f32 v167, v64, v65
	s_waitcnt lgkmcnt(3)
	v_mfma_f32_32x32x16_bf16 v[80:95], v[182:185], v[126:129], v[80:95]
	v_exp_f32_e32 v64, v68
	v_exp_f32_e32 v65, v69
	v_add_f32_e32 v66, v64, v66
	v_add_f32_e32 v66, v65, v66
	v_cvt_pk_bf16_f32 v168, v64, v65
	v_mfma_f32_32x32x16_bf16 v[80:95], v[174:177], v[130:133], v[80:95]
	v_exp_f32_e32 v64, v70
	v_exp_f32_e32 v65, v71
	v_add_f32_e32 v66, v64, v66
	v_add_f32_e32 v174, v65, v66
	v_cvt_pk_bf16_f32 v169, v64, v65
	s_waitcnt lgkmcnt(0)
	v_mfma_f32_32x32x16_bf16 v[80:95], v[204:207], v[134:137], v[80:95]
	ds_read_b128 v[64:67], v222 offset:13376
	ds_read_b128 v[68:71], v222 offset:13408
	ds_read_b128 v[180:183], v222 offset:17984
	ds_read_b128 v[222:225], v222 offset:18016
	v_exp_f32_e32 v72, v72
	v_exp_f32_e32 v73, v73
	v_add_f32_e32 v174, v72, v174
	v_add_f32_e32 v175, v73, v174
	v_cvt_pk_bf16_f32 v174, v72, v73
	v_mfma_f32_32x32x16_bf16 v[80:95], v[208:211], v[154:157], v[80:95]
	v_exp_f32_e32 v72, v74
	v_exp_f32_e32 v73, v75
	v_add_f32_e32 v74, v72, v175
	v_add_f32_e32 v74, v73, v74
	v_cvt_pk_bf16_f32 v175, v72, v73
	v_mfma_f32_32x32x16_bf16 v[80:95], v[218:221], v[158:161], v[80:95]
	v_exp_f32_e32 v72, v76
	v_exp_f32_e32 v73, v77
	v_add_f32_e32 v74, v72, v74
	v_add_f32_e32 v74, v73, v74
	v_cvt_pk_bf16_f32 v176, v72, v73
	s_waitcnt lgkmcnt(0)
	v_mfma_f32_32x32x16_bf16 v[16:31], v[64:67], v[162:165], v[16:31]
	v_exp_f32_e32 v64, v78
	v_exp_f32_e32 v65, v79
	v_add_f32_e32 v66, v64, v74
	v_add_f32_e32 v204, v65, v66
	v_cvt_pk_bf16_f32 v177, v64, v65
	v_mfma_f32_32x32x16_bf16 v[0:15], v[180:183], v[162:165], v[0:15]
	ds_read_b128 v[64:67], v199 offset:29184
	ds_read_b128 v[180:183], v199 offset:29216
	ds_read_b128 v[208:211], v199 offset:29248
	v_cmp_nge_f32_e32 vcc, s48, v204
	v_mfma_f32_32x32x16_bf16 v[16:31], v[68:71], v[170:173], v[16:31]
	v_mfma_f32_32x32x16_bf16 v[0:15], v[222:225], v[170:173], v[0:15]
	v_mad_u32_u24 v68, v187, s69, v186
	v_add_u32_e32 v206, s76, v68
	v_exp_f32_e32 v68, v80
	v_exp_f32_e32 v69, v81
	s_nop 0
	v_add_f32_e32 v70, v69, v68
	v_cvt_pk_bf16_f32 v162, v68, v69
	v_exp_f32_e32 v80, v82
	ds_read_b128 v[170:173], v199 offset:29280
	ds_read_b128 v[218:221], v199 offset:29312
	ds_read_b128 v[222:225], v199 offset:29344
	v_exp_f32_e32 v81, v83
	v_add_f32_e32 v82, v80, v70
	s_waitcnt lgkmcnt(3)
	v_mfma_f32_32x32x16_bf16 v[64:79], v[64:67], v[98:101], 0
	v_add_f32_e32 v82, v81, v82
	v_cvt_pk_bf16_f32 v163, v80, v81
	v_mfma_f32_32x32x16_bf16 v[64:79], v[180:183], v[102:105], v[64:79]
	v_exp_f32_e32 v80, v84
	v_exp_f32_e32 v81, v85
	v_add_f32_e32 v82, v80, v82
	v_add_f32_e32 v82, v81, v82
	v_cvt_pk_bf16_f32 v164, v80, v81
	v_mfma_f32_32x32x16_bf16 v[64:79], v[208:211], v[106:109], v[64:79]
	v_exp_f32_e32 v80, v86
	v_exp_f32_e32 v81, v87
	v_add_f32_e32 v82, v80, v82
	v_add_f32_e32 v184, v81, v82
	v_cvt_pk_bf16_f32 v165, v80, v81
	s_waitcnt lgkmcnt(0)
	v_mfma_f32_32x32x16_bf16 v[64:79], v[170:173], v[110:113], v[64:79]
	ds_read_b128 v[80:83], v206 offset:35840
	ds_read_b128 v[84:87], v206 offset:35872
	ds_read_b128 v[180:183], v206 offset:40448
	ds_read_b128 v[208:211], v206 offset:40480
	v_exp_f32_e32 v88, v88
	v_exp_f32_e32 v89, v89
	v_add_f32_e32 v170, v88, v184
	v_add_f32_e32 v171, v89, v170
	v_cvt_pk_bf16_f32 v170, v88, v89
	v_mfma_f32_32x32x16_bf16 v[64:79], v[218:221], v[114:117], v[64:79]
	v_exp_f32_e32 v88, v90
	v_exp_f32_e32 v89, v91
	v_add_f32_e32 v90, v88, v171
	v_add_f32_e32 v90, v89, v90
	v_cvt_pk_bf16_f32 v171, v88, v89
	v_mfma_f32_32x32x16_bf16 v[64:79], v[222:225], v[118:121], v[64:79]
	v_exp_f32_e32 v88, v92
	v_exp_f32_e32 v89, v93
	v_add_f32_e32 v90, v88, v90
	v_add_f32_e32 v90, v89, v90
	v_cvt_pk_bf16_f32 v172, v88, v89
	s_waitcnt lgkmcnt(0)
	v_mfma_f32_32x32x16_bf16 v[48:63], v[80:83], v[166:169], v[48:63]
	v_exp_f32_e32 v80, v94
	v_exp_f32_e32 v81, v95
	v_add_f32_e32 v82, v80, v90
	v_add_f32_e32 v205, v81, v82
	v_cvt_pk_bf16_f32 v173, v80, v81
	v_mfma_f32_32x32x16_bf16 v[32:47], v[180:183], v[166:169], v[32:47]
	ds_read_b128 v[80:83], v199 offset:29184
	ds_read_b128 v[166:169], v199 offset:29216
	ds_read_b128 v[182:185], v199 offset:29248
	s_or_b64 s[8:9], s[6:7], vcc
	v_cmp_nge_f32_e32 vcc, s48, v205
	v_pk_add_f32 v[204:205], v[178:179], v[204:205]
	v_mfma_f32_32x32x16_bf16 v[48:63], v[84:87], v[174:177], v[48:63]
	v_exp_f32_e32 v64, v64
	v_exp_f32_e32 v65, v65
	s_nop 0
	v_add_f32_e32 v84, v65, v64
	v_cvt_pk_bf16_f32 v178, v64, v65
	v_exp_f32_e32 v64, v66
	v_exp_f32_e32 v65, v67
	v_add_f32_e32 v66, v64, v84
	v_mfma_f32_32x32x16_bf16 v[32:47], v[208:211], v[174:177], v[32:47]
	ds_read_b128 v[174:177], v199 offset:29280
	ds_read_b128 v[208:211], v199 offset:29312
	ds_read_b128 v[218:221], v199 offset:29344
	s_waitcnt lgkmcnt(3)
	v_mfma_f32_32x32x16_bf16 v[80:95], v[80:83], v[122:125], 0
	v_add_f32_e32 v66, v65, v66
	v_cvt_pk_bf16_f32 v179, v64, v65
	v_mfma_f32_32x32x16_bf16 v[80:95], v[166:169], v[126:129], v[80:95]
	v_exp_f32_e32 v64, v68
	v_exp_f32_e32 v65, v69
	v_add_f32_e32 v66, v64, v66
	v_add_f32_e32 v66, v65, v66
	v_cvt_pk_bf16_f32 v180, v64, v65
	v_mfma_f32_32x32x16_bf16 v[80:95], v[182:185], v[130:133], v[80:95]
	v_exp_f32_e32 v64, v70
	v_exp_f32_e32 v65, v71
	v_add_f32_e32 v66, v64, v66
	v_add_f32_e32 v182, v65, v66
	v_cvt_pk_bf16_f32 v181, v64, v65
	s_waitcnt lgkmcnt(0)
	v_mfma_f32_32x32x16_bf16 v[80:95], v[174:177], v[134:137], v[80:95]
	ds_read_b128 v[64:67], v206 offset:35840
	ds_read_b128 v[68:71], v206 offset:35872
	ds_read_b128 v[166:169], v206 offset:40448
	ds_read_b128 v[222:225], v206 offset:40480
	v_exp_f32_e32 v72, v72
	v_exp_f32_e32 v73, v73
	v_add_f32_e32 v174, v72, v182
	v_add_f32_e32 v174, v73, v174
	v_cvt_pk_bf16_f32 v182, v72, v73
	v_mfma_f32_32x32x16_bf16 v[80:95], v[208:211], v[154:157], v[80:95]
	v_exp_f32_e32 v72, v74
	v_exp_f32_e32 v73, v75
	v_add_f32_e32 v74, v72, v174
	v_add_f32_e32 v74, v73, v74
	v_cvt_pk_bf16_f32 v183, v72, v73
	v_mfma_f32_32x32x16_bf16 v[80:95], v[218:221], v[158:161], v[80:95]
	v_exp_f32_e32 v72, v76
	v_exp_f32_e32 v73, v77
	v_add_f32_e32 v74, v72, v74
	v_add_f32_e32 v74, v73, v74
	v_cvt_pk_bf16_f32 v184, v72, v73
	s_waitcnt lgkmcnt(0)
	v_mfma_f32_32x32x16_bf16 v[16:31], v[64:67], v[162:165], v[16:31]
	v_exp_f32_e32 v64, v78
	v_exp_f32_e32 v65, v79
	v_add_f32_e32 v66, v64, v74
	v_add_f32_e32 v226, v65, v66
	v_cvt_pk_bf16_f32 v185, v64, v65
	v_mfma_f32_32x32x16_bf16 v[0:15], v[166:169], v[162:165], v[0:15]
	s_mulk_i32 s10, 0x5800
	v_add_u32_e32 v199, s10, v242
	ds_read_b128 v[64:67], v199
	ds_read_b128 v[164:167], v199 offset:32
	ds_read_b128 v[174:177], v199 offset:64
	v_cmp_nge_f32_e64 s[6:7], s48, v226
	v_mfma_f32_32x32x16_bf16 v[16:31], v[68:71], v[170:173], v[16:31]
	v_exp_f32_e32 v68, v80
	v_exp_f32_e32 v69, v81
	s_nop 0
	v_add_f32_e32 v70, v69, v68
	v_cvt_pk_bf16_f32 v162, v68, v69
	v_exp_f32_e32 v80, v82
	v_exp_f32_e32 v81, v83
	v_add_f32_e32 v82, v80, v70
	v_mfma_f32_32x32x16_bf16 v[0:15], v[222:225], v[170:173], v[0:15]
	s_or_b64 s[8:9], s[8:9], vcc
	ds_read_b128 v[168:171], v199 offset:96
	ds_read_b128 v[208:211], v199 offset:128
	ds_read_b128 v[218:221], v199 offset:160
	s_waitcnt lgkmcnt(3)
	v_mfma_f32_32x32x16_bf16 v[64:79], v[64:67], v[98:101], 0
	v_add_f32_e32 v82, v81, v82
	v_cvt_pk_bf16_f32 v163, v80, v81
	v_mfma_f32_32x32x16_bf16 v[64:79], v[164:167], v[102:105], v[64:79]
	v_exp_f32_e32 v80, v84
	v_exp_f32_e32 v81, v85
	v_add_f32_e32 v82, v80, v82
	v_add_f32_e32 v82, v81, v82
	v_cvt_pk_bf16_f32 v164, v80, v81
	v_mfma_f32_32x32x16_bf16 v[64:79], v[174:177], v[106:109], v[64:79]
	v_exp_f32_e32 v80, v86
	v_exp_f32_e32 v81, v87
	v_add_f32_e32 v82, v80, v82
	v_add_f32_e32 v166, v81, v82
	v_cvt_pk_bf16_f32 v165, v80, v81
	s_waitcnt lgkmcnt(0)
	v_mfma_f32_32x32x16_bf16 v[64:79], v[168:171], v[110:113], v[64:79]
	ds_read_b128 v[80:83], v206 offset:35904
	ds_read_b128 v[84:87], v206 offset:35936
	ds_read_b128 v[222:225], v206 offset:40512
	ds_read_b128 v[246:249], v206 offset:40544
	v_exp_f32_e32 v88, v88
	v_exp_f32_e32 v89, v89
	v_add_f32_e32 v166, v88, v166
	v_add_f32_e32 v167, v89, v166
	v_cvt_pk_bf16_f32 v166, v88, v89
	v_mfma_f32_32x32x16_bf16 v[64:79], v[208:211], v[114:117], v[64:79]
	v_exp_f32_e32 v88, v90
	v_exp_f32_e32 v89, v91
	v_add_f32_e32 v90, v88, v167
	v_add_f32_e32 v90, v89, v90
	v_cvt_pk_bf16_f32 v167, v88, v89
	v_mfma_f32_32x32x16_bf16 v[64:79], v[218:221], v[118:121], v[64:79]
	v_exp_f32_e32 v88, v92
	v_exp_f32_e32 v89, v93
	v_add_f32_e32 v90, v88, v90
	v_add_f32_e32 v90, v89, v90
	v_cvt_pk_bf16_f32 v168, v88, v89
	s_waitcnt lgkmcnt(0)
	v_mfma_f32_32x32x16_bf16 v[48:63], v[80:83], v[178:181], v[48:63]
	v_exp_f32_e32 v80, v94
	v_exp_f32_e32 v81, v95
	v_add_f32_e32 v82, v80, v90
	v_add_f32_e32 v227, v81, v82
	v_cvt_pk_bf16_f32 v169, v80, v81
	v_mfma_f32_32x32x16_bf16 v[32:47], v[222:225], v[178:181], v[32:47]
	ds_read_b128 v[80:83], v199
	ds_read_b128 v[174:177], v199 offset:32
	ds_read_b128 v[170:173], v199 offset:64
	s_or_b64 s[6:7], s[8:9], s[6:7]
	v_cmp_nge_f32_e32 vcc, s48, v227
	s_or_b64 s[6:7], s[6:7], vcc
	s_cmp_lg_u64 s[6:7], 0
	s_cselect_b64 s[6:7], -1, 0
	s_or_b64 s[42:43], s[42:43], s[6:7]
	v_mfma_f32_32x32x16_bf16 v[48:63], v[84:87], v[182:185], v[48:63]
	v_add_f32_e64 v204, v204, v226
	v_add_f32_e64 v205, v205, v227
	v_mfma_f32_32x32x16_bf16 v[32:47], v[246:249], v[182:185], v[32:47]
	s_waitcnt lgkmcnt(0)
	s_barrier
	s_add_u32 s40, s40, 0x40000
	s_mov_b64 s[6:7], 0x2000
	s_addc_u32 s41, s41, 0
	v_lshl_add_u64 v[202:203], v[202:203], 0, s[6:7]
	s_and_b64 vcc, exec, s[44:45]
	s_cbranch_vccnz .LBB0_937
	s_mov_b32 s61, s30
	s_branch .LBB0_923
